# FFN1 GEMM: first K-iteration after a full unit waits only for the prologue stages (vmcnt 16 / 10), not for the epilogue stores
# speedup vs baseline: 1.0120x; 1.0021x over previous
;     __device__ __forceinline__ bool idx(int i, int& Lp, int& half) const {
;         const int R = n / G, T = n % G; long L; half = 0;
;         if (i == R && T > 0 && 2 * T <= G) { if (c >= 2 * T) return false; L = (long)R * G + (c >> 1); half = 1 + (c & 1); }
;         else { L = (long)i * G + c; if (L >= n) return false; }
; __global__ void __launch_bounds__(512, 2) hybrid_fwd(Params p_unused) {
;     ...
;         if (PHM & 4096) { const Params p = ldp(); SchedFfn1 S{{nM * 22, G, c}, p.ws, (size_t)0 * WSET}; g8::EpiSwiglu E; g8::gemm_phase(wv, lds, 1024, S, E); }
.LBB0_1288:
	s_or_b64 exec, exec, s[6:7]
	s_mov_b32 s101, 0
	s_mov_b64 s[0:1], s[90:91]
	s_waitcnt lgkmcnt(0)
	s_barrier
	s_load_dwordx2 s[18:19], s[0:1], 0xa8
	s_mul_i32 s56, s28, 22
	v_readlane_b32 s1, v254, 1
	s_mul_hi_u32 s1, s56, s1
	v_readlane_b32 s6, v254, 4
	s_mul_i32 s3, s1, s6
	s_sub_i32 s3, s56, s3
	s_add_i32 s4, s1, 1
	s_sub_i32 s5, s3, s6
	s_cmp_ge_u32 s3, s6
	s_cselect_b32 s1, s4, s1
	s_cselect_b32 s3, s5, s3
	s_add_i32 s4, s1, 1
	s_cmp_ge_u32 s3, s6
	s_cselect_b32 s1, s4, s1
	s_xor_b32 s1, s1, s45
	s_sub_i32 s1, s1, s45
	s_mul_i32 s3, s1, s44
	s_sub_i32 s8, s56, s3
	s_cmp_lg_u32 s1, 0
	v_mbcnt_lo_u32_b32 v0, -1, 0
	v_mbcnt_hi_u32_b32 v0, -1, v0
	s_cselect_b64 s[6:7], -1, 0
	v_add_u32_e32 v2, s89, v0
	s_and_b64 vcc, exec, s[6:7]
	v_readfirstlane_b32 s0, v2
	s_cbranch_vccnz .LBB0_1292
	s_lshl_b32 s3, s8, 1
	s_cmp_le_i32 s3, s44
	s_cbranch_scc0 .LBB0_1291
	s_cmp_lt_i32 s96, s3
	s_mov_b64 s[6:7], 0
	s_cselect_b64 s[4:5], -1, 0
	s_branch .LBB0_1293

; __device__ __forceinline__ unsigned pk_bf16(float lo, float hi) { unsigned r; asm volatile("v_cvt_pk_bf16_f32 %0, %1, %2" : "=v"(r) : "v"(lo), "v"(hi)); return r; }
;     __device__ __forceinline__ void operator()(const f32x4 (&acc)[2][2][4][2], const Unit& u, int wr, int wc, int fr, int fq) const {
;         const int row0 = wr * 64 + fr, col0 = wc * 32 + 8 * fq;
; #pragma unroll
;         for (int ai = 0; ai < 2; ++ai) if (ai == 0 || u.half == 0)
; #pragma unroll
;             for (int m = 0; m < 4; ++m) { bf16_t* rowp = (bf16_t*)u.o + (size_t)(row0 + ai * HALF + m * 16) * u.ldo + col0; float r[8];
; #pragma unroll
;                 for (int bj = 0; bj < 2; ++bj) { const f32x4 a = acc[ai][bj][m][0], b = acc[ai][bj][m][1];
; #pragma unroll
;                     for (int e = 0; e < 4; ++e) r[bj * 4 + e] = a[e] * b[e] * __builtin_amdgcn_rcpf(1.f + __expf(-a[e])); }
;                 u32x4 w; w.x = pk_bf16(r[0], r[1]); w.y = pk_bf16(r[2], r[3]); w.z = pk_bf16(r[4], r[5]); w.w = pk_bf16(r[6], r[7]); st16_wt(rowp, w); }
;     }
.LBB0_1304:
	s_mov_b32 s101, 0
	v_mul_f32_e32 v128, v124, v128
	v_mul_f32_e32 v124, 0xbfb8aa3b, v124
	v_exp_f32_e32 v124, v124
	v_mul_f32_e32 v112, v108, v112
	v_mul_f32_e32 v108, 0xbfb8aa3b, v108
	v_exp_f32_e32 v108, v108
	v_add_f32_e32 v124, 1.0, v124
	v_rcp_f32_e32 v124, v124
	v_mul_f32_e32 v96, v92, v96
	v_mul_f32_e32 v92, 0xbfb8aa3b, v92
	v_exp_f32_e32 v92, v92
	v_add_f32_e32 v108, 1.0, v108
	v_rcp_f32_e32 v108, v108
	v_mul_f32_e32 v124, v128, v124
	v_mul_f32_e32 v128, v125, v129
	v_mul_f32_e32 v125, 0xbfb8aa3b, v125
	v_exp_f32_e32 v125, v125
	v_add_f32_e32 v92, 1.0, v92
	v_rcp_f32_e32 v92, v92
	v_mul_f32_e32 v108, v112, v108
	v_mul_f32_e32 v112, v109, v113
	v_mul_f32_e32 v109, 0xbfb8aa3b, v109
	v_exp_f32_e32 v109, v109
	v_add_f32_e32 v125, 1.0, v125
	v_rcp_f32_e32 v125, v125
	v_mul_f32_e32 v92, v96, v92
	v_mul_f32_e32 v96, v93, v97
	v_mul_f32_e32 v93, 0xbfb8aa3b, v93
	v_exp_f32_e32 v93, v93
	v_add_f32_e32 v109, 1.0, v109
	v_rcp_f32_e32 v109, v109
	v_mul_f32_e32 v125, v128, v125
	v_mul_f32_e32 v128, v126, v130
	v_mul_f32_e32 v126, 0xbfb8aa3b, v126
	v_exp_f32_e32 v126, v126
	v_add_f32_e32 v93, 1.0, v93
	v_rcp_f32_e32 v93, v93
	v_mul_f32_e32 v109, v112, v109
	v_mul_f32_e32 v112, v110, v114
	v_mul_f32_e32 v110, 0xbfb8aa3b, v110
	v_exp_f32_e32 v110, v110
	v_add_f32_e32 v126, 1.0, v126
	v_rcp_f32_e32 v126, v126
	v_mul_f32_e32 v93, v96, v93
	v_mul_f32_e32 v96, v94, v98
	v_mul_f32_e32 v94, 0xbfb8aa3b, v94
	v_exp_f32_e32 v94, v94
	v_add_f32_e32 v110, 1.0, v110
	v_rcp_f32_e32 v110, v110
	v_mul_f32_e32 v126, v128, v126
	v_mul_f32_e32 v128, v127, v131
	v_mul_f32_e32 v127, 0xbfb8aa3b, v127
	v_mul_f32_e32 v120, v116, v120
	v_mul_f32_e32 v116, 0xbfb8aa3b, v116
	v_exp_f32_e32 v127, v127
	v_exp_f32_e32 v116, v116
	v_add_f32_e32 v94, 1.0, v94
	v_rcp_f32_e32 v94, v94
	v_mul_f32_e32 v110, v112, v110
	v_mul_f32_e32 v112, v111, v115
	v_mul_f32_e32 v111, 0xbfb8aa3b, v111
	v_mul_f32_e32 v104, v100, v104
	v_mul_f32_e32 v100, 0xbfb8aa3b, v100
	v_exp_f32_e32 v111, v111
	v_exp_f32_e32 v100, v100
	v_add_f32_e32 v127, 1.0, v127
	v_add_f32_e32 v116, 1.0, v116
	v_rcp_f32_e32 v127, v127
	v_rcp_f32_e32 v116, v116
	v_mul_f32_e32 v94, v96, v94
	v_mul_f32_e32 v96, v95, v99
	v_mul_f32_e32 v95, 0xbfb8aa3b, v95
	v_mul_f32_e32 v88, v84, v88
	v_mul_f32_e32 v84, 0xbfb8aa3b, v84
	v_exp_f32_e32 v95, v95
	v_exp_f32_e32 v84, v84
	v_add_f32_e32 v111, 1.0, v111
	v_add_f32_e32 v100, 1.0, v100
	v_rcp_f32_e32 v111, v111
	v_rcp_f32_e32 v100, v100
	v_mul_f32_e32 v68, v72, v68
	v_mul_f32_e32 v72, 0xbfb8aa3b, v72
	v_mul_f32_e32 v127, v128, v127
	v_mul_f32_e32 v128, v120, v116
	v_mul_f32_e32 v116, v117, v121
	v_mul_f32_e32 v117, 0xbfb8aa3b, v117
	v_mul_f32_e32 v80, v76, v80
	v_mul_f32_e32 v76, 0xbfb8aa3b, v76
	v_exp_f32_e32 v72, v72
	v_exp_f32_e32 v117, v117
	v_add_f32_e32 v95, 1.0, v95
	v_add_f32_e32 v84, 1.0, v84
	v_exp_f32_e32 v76, v76
	v_rcp_f32_e32 v95, v95
	v_rcp_f32_e32 v84, v84
	v_mul_f32_e32 v111, v112, v111
	v_mul_f32_e32 v112, v104, v100
	v_mul_f32_e32 v100, v101, v105
	v_mul_f32_e32 v101, 0xbfb8aa3b, v101
	v_exp_f32_e32 v101, v101
	v_add_f32_e32 v72, 1.0, v72
	v_add_f32_e32 v117, 1.0, v117
	v_add_f32_e32 v76, 1.0, v76
	v_rcp_f32_e32 v72, v72
	v_rcp_f32_e32 v117, v117
	v_mul_f32_e32 v95, v96, v95
	v_mul_f32_e32 v96, v88, v84
	v_mul_f32_e32 v84, v85, v89
	v_mul_f32_e32 v85, 0xbfb8aa3b, v85
	v_rcp_f32_e32 v76, v76
	v_exp_f32_e32 v85, v85
	v_add_f32_e32 v101, 1.0, v101
	v_rcp_f32_e32 v101, v101
	v_mul_f32_e32 v72, v68, v72
	v_mul_f32_e32 v68, v73, v69
	v_mul_f32_e32 v69, 0xbfb8aa3b, v73
	v_mul_f32_e32 v129, v116, v117
	v_mul_f32_e32 v117, 0xbfb8aa3b, v118
	v_mul_f32_e32 v76, v80, v76
	v_mul_f32_e32 v80, v77, v81
	v_mul_f32_e32 v77, 0xbfb8aa3b, v77
	v_exp_f32_e32 v69, v69
	v_exp_f32_e32 v117, v117
	v_add_f32_e32 v85, 1.0, v85
	v_exp_f32_e32 v77, v77
	v_rcp_f32_e32 v85, v85
	v_mul_f32_e32 v113, v100, v101
	v_mul_f32_e32 v101, 0xbfb8aa3b, v102
	v_exp_f32_e32 v101, v101
	v_add_f32_e32 v69, 1.0, v69
	v_add_f32_e32 v117, 1.0, v117
	v_add_f32_e32 v77, 1.0, v77
	v_rcp_f32_e32 v69, v69
	v_rcp_f32_e32 v117, v117
	v_mul_f32_e32 v97, v84, v85
	v_mul_f32_e32 v85, 0xbfb8aa3b, v86
	v_rcp_f32_e32 v77, v77
	v_exp_f32_e32 v85, v85
	v_add_f32_e32 v101, 1.0, v101
	v_mul_f32_e32 v116, v118, v122
	v_rcp_f32_e32 v101, v101
	v_mul_f32_e32 v73, v68, v69
	v_mul_f32_e32 v69, 0xbfb8aa3b, v74
	v_mul_f32_e32 v122, v116, v117
	v_mul_f32_e32 v117, 0xbfb8aa3b, v119
	v_mul_f32_e32 v77, v80, v77
	v_mul_f32_e32 v80, v78, v82
	v_mul_f32_e32 v78, 0xbfb8aa3b, v78
	v_exp_f32_e32 v69, v69
	v_exp_f32_e32 v117, v117
	v_add_f32_e32 v85, 1.0, v85
	v_exp_f32_e32 v78, v78
	v_mul_f32_e32 v100, v102, v106
	v_rcp_f32_e32 v85, v85
	v_mul_f32_e32 v106, v100, v101
	v_mul_f32_e32 v101, 0xbfb8aa3b, v103
	v_exp_f32_e32 v101, v101
	v_add_f32_e32 v69, 1.0, v69
	v_add_f32_e32 v117, 1.0, v117
	v_mul_f32_e32 v84, v86, v90
	v_add_f32_e32 v78, 1.0, v78
	v_rcp_f32_e32 v69, v69
	v_mbcnt_lo_u32_b32 v0, -1, 0
	v_mbcnt_hi_u32_b32 v0, -1, v0
	v_rcp_f32_e32 v117, v117
	v_mul_f32_e32 v90, v84, v85
	v_mul_f32_e32 v85, 0xbfb8aa3b, v87
	v_rcp_f32_e32 v78, v78
	s_waitcnt lgkmcnt(0)
; __device__ __forceinline__ unsigned pk_bf16(float lo, float hi) { unsigned r; asm volatile("v_cvt_pk_bf16_f32 %0, %1, %2" : "=v"(r) : "v"(lo), "v"(hi)); return r; }
;     __device__ __forceinline__ void operator()(const f32x4 (&acc)[2][2][4][2], const Unit& u, int wr, int wc, int fr, int fq) const {
;     ...
;             for (int m = 0; m < 4; ++m) { bf16_t* rowp = (bf16_t*)u.o + (size_t)(row0 + ai * HALF + m * 16) * u.ldo + col0; float r[8];
; #pragma unroll
;                 for (int bj = 0; bj < 2; ++bj) { const f32x4 a = acc[ai][bj][m][0], b = acc[ai][bj][m][1];
; #pragma unroll
;                     for (int e = 0; e < 4; ++e) r[bj * 4 + e] = a[e] * b[e] * __builtin_amdgcn_rcpf(1.f + __expf(-a[e])); }
;                 u32x4 w; w.x = pk_bf16(r[0], r[1]); w.y = pk_bf16(r[2], r[3]); w.z = pk_bf16(r[4], r[5]); w.w = pk_bf16(r[6], r[7]); st16_wt(rowp, w); }
	v_and_or_b32 v132, v0, 15, s50
	v_lshrrev_b32_e32 v0, 1, v0
	v_exp_f32_e32 v85, v85
	v_and_or_b32 v0, v0, 24, s51
	v_mov_b64_e32 v[2:3], s[30:31]
	s_movk_i32 s34, 0x1600
	v_add_f32_e32 v101, 1.0, v101
	v_mul_f32_e32 v68, v74, v70
	v_mad_i64_i32 v[134:135], s[4:5], v132, s34, v[2:3]
	v_mul_f32_e32 v116, v119, v123
	v_lshlrev_b32_e32 v0, 1, v0
	v_rcp_f32_e32 v101, v101
	v_mul_f32_e32 v74, v68, v69
	v_mul_f32_e32 v69, 0xbfb8aa3b, v75
	v_mul_f32_e32 v119, v116, v117
	v_lshl_add_u64 v[120:121], v[134:135], 0, v[0:1]
	v_cvt_pk_bf16_f32 v116, v124, v125
	v_mul_f32_e32 v78, v80, v78
	v_mul_f32_e32 v80, v79, v83
	v_mul_f32_e32 v79, 0xbfb8aa3b, v79
	v_exp_f32_e32 v69, v69
	v_cvt_pk_bf16_f32 v117, v126, v127
	v_cvt_pk_bf16_f32 v118, v128, v129
	v_cvt_pk_bf16_f32 v119, v122, v119
	global_store_dwordx4 v[120:121], v[116:119], off
	v_add_f32_e32 v85, 1.0, v85
	v_exp_f32_e32 v79, v79
	v_or_b32_e32 v116, 16, v132
	v_mad_i64_i32 v[116:117], s[4:5], v116, s34, v[2:3]
	v_mul_f32_e32 v100, v103, v107
	v_rcp_f32_e32 v85, v85
	v_mul_f32_e32 v103, v100, v101
	v_lshl_add_u64 v[104:105], v[116:117], 0, v[0:1]
	v_cvt_pk_bf16_f32 v100, v108, v109
	v_cvt_pk_bf16_f32 v101, v110, v111
	v_cvt_pk_bf16_f32 v102, v112, v113
	v_cvt_pk_bf16_f32 v103, v106, v103
	global_store_dwordx4 v[104:105], v[100:103], off
	v_add_f32_e32 v69, 1.0, v69
	v_mul_f32_e32 v84, v87, v91
	v_or_b32_e32 v100, 32, v132
	v_mad_i64_i32 v[100:101], s[4:5], v100, s34, v[2:3]
	v_add_f32_e32 v79, 1.0, v79
	v_rcp_f32_e32 v69, v69
	v_mul_f32_e32 v87, v84, v85
	v_lshl_add_u64 v[88:89], v[100:101], 0, v[0:1]
	v_cvt_pk_bf16_f32 v84, v92, v93
	v_rcp_f32_e32 v79, v79
	v_cvt_pk_bf16_f32 v85, v94, v95
	v_cvt_pk_bf16_f32 v86, v96, v97
	v_cvt_pk_bf16_f32 v87, v90, v87
	global_store_dwordx4 v[88:89], v[84:87], off
	v_mul_f32_e32 v68, v75, v71
	v_mul_f32_e32 v71, v68, v69
	v_or_b32_e32 v84, 48, v132
	v_mad_i64_i32 v[2:3], s[4:5], v84, s34, v[2:3]
	v_lshl_add_u64 v[2:3], v[2:3], 0, v[0:1]
	s_and_b64 vcc, exec, s[14:15]
	v_mul_f32_e32 v79, v80, v79
	v_cvt_pk_bf16_f32 v68, v76, v77
	v_cvt_pk_bf16_f32 v69, v78, v79
	v_cvt_pk_bf16_f32 v70, v72, v73
	v_cvt_pk_bf16_f32 v71, v74, v71
	global_store_dwordx4 v[2:3], v[68:71], off
	s_cbranch_vccz .LBB0_1329

; template <class Epi, class Sched>
; __device__ __forceinline__ void gemm_phase(int wv, LAS unsigned char* lds, const int K, const Sched& S, const Epi& E) {
;     ...
;         for (int t = 0; t < nt; t += 2) {
;             const bool last = (t == nt - 2);
;             const char* a1 = cA + (size_t)(t + 1) * kstep;
;             const char* a2 = last ? nA : cA + (size_t)(t + 2) * kstep; const char* b2 = last ? nB : cB + (size_t)(t + 2) * kstep;
;             const char* a3 = a2 + kstep; const char* b3 = b2 + kstep;
.LBB0_1316:
	s_mov_b32 s101, 0
	s_add_i32 s75, s75, 2
	s_add_u32 s36, s36, 0x100
	s_addc_u32 s37, s37, 0
	s_add_u32 s4, s4, 0x100
	s_addc_u32 s5, s5, 0
	s_cmp_gt_u32 s75, 13
	s_barrier
	s_cbranch_scc1 .LBB0_1304

; #define G8_STAGE(bufoff, gbase, voff) do { _Pragma("unroll") for (int _i = 0; _i < 2; ++_i) \
;         __builtin_amdgcn_global_load_lds((const unsigned*)((const char*)(gbase) + (voff)[_i]), (LAS unsigned*)(lds + (bufoff) + ldsw + _i * 8192), 16, 0, 0); } while (0)
; #define G8_LDA(dst, b, h) do { _Pragma("unroll") for (int m = 0; m < 4; ++m) _Pragma("unroll") for (int k = 0; k < 2; ++k) dst[m][k] = *(const LAS bf16x8*)(lds + G8_SA(b, h) + aoff + m * 2048 + k * 1024); } while (0)
; #define G8_LDB(dst, b, h) do { _Pragma("unroll") for (int n = 0; n < 2; ++n) _Pragma("unroll") for (int k = 0; k < 2; ++k) dst[n][k] = *(const LAS bf16x8*)(lds + G8_SB(b, h) + boff + n * 2048 + k * 1024); } while (0)
; #define G8_MMA(ai, bj, At, Bt) do { __builtin_amdgcn_s_setprio(1); _Pragma("unroll") for (int m = 0; m < 4; ++m) _Pragma("unroll") for (int n = 0; n < 2; ++n) _Pragma("unroll") for (int k = 0; k < 2; ++k) \
;         acc[ai][bj][m][n] = __builtin_amdgcn_mfma_f32_16x16x32_bf16(Bt[n][k], At[m][k], acc[ai][bj][m][n], 0, 0, 0); __builtin_amdgcn_s_setprio(0); } while (0)
; #define G8_WAIT_V(n) asm volatile("s_waitcnt vmcnt(" #n ")" ::: "memory")
; #define G8_WAIT_L(n) asm volatile("s_waitcnt lgkmcnt(" #n ")" ::: "memory")
; #define G8_BAR __builtin_amdgcn_s_barrier()
; #define G8_SCHED __builtin_amdgcn_sched_barrier(0)
; template <class Epi, class Sched>
; __device__ __forceinline__ void gemm_phase(int wv, LAS unsigned char* lds, const int K, const Sched& S, const Epi& E) {
;     ...
;             G8_STAGE(G8_SB(0, 1), b2 + hstep, voffB);
;             G8_WAIT_V(6); G8_BAR; if (full) G8_MMA(1, 1, At, B1); G8_BAR;
;             G8_LDB(B0, 1, 0); G8_SCHED; G8_LDA(At, 1, 0); G8_STAGE(G8_SA(0, 1), a2 + hstep, voffA);
;             G8_WAIT_L(8); G8_BAR; G8_WAIT_L(0); G8_MMA(0, 0, At, B0); G8_BAR; G8_SCHED;
;             G8_LDB(B1, 1, 1); G8_STAGE(G8_SB(1, 0), b3, voffB);
;             G8_BAR; G8_WAIT_L(0); G8_MMA(0, 1, At, B1); G8_BAR;
;             if (full) G8_LDA(At, 1, 1); G8_STAGE(G8_SA(1, 0), a3, voffA);
;             G8_BAR; G8_WAIT_L(0); if (full) G8_MMA(1, 0, At, B0); G8_BAR; G8_SCHED;
.LBB0_1321:
	s_barrier
	s_add_u32 s76, s38, 0x40000
	s_addc_u32 s77, s39, 0
	s_mov_b32 m0, s46
	v_lshl_add_u64 v[180:181], s[76:77], 0, v[206:207]
	global_load_lds_dwordx4 v[180:181], off
	v_lshl_add_u64 v[180:181], s[76:77], 0, v[208:209]
	s_mov_b32 m0, s47
	s_and_b64 vcc, exec, s[14:15]
	global_load_lds_dwordx4 v[180:181], off
	s_cmp_eq_u32 s101, 1
	s_cbranch_scc1 .Lp8rx_a
	s_waitcnt vmcnt(6)
	s_branch .Lp8rx_b
.Lp8rx_a:
	s_waitcnt vmcnt(16)
.Lp8rx_b:
	s_barrier
	s_cbranch_vccnz .LBB0_1323
	s_setprio 1
	s_waitcnt lgkmcnt(0)
	v_mfma_f32_16x16x32_bf16 v[52:55], v[164:167], v[144:147], v[52:55]
	v_mfma_f32_16x16x32_bf16 v[56:59], v[172:175], v[144:147], v[56:59]
	v_mfma_f32_16x16x32_bf16 v[36:39], v[164:167], v[140:143], v[36:39]
	v_mfma_f32_16x16x32_bf16 v[40:43], v[172:175], v[140:143], v[40:43]
	v_mfma_f32_16x16x32_bf16 v[20:23], v[164:167], v[136:139], v[20:23]
	v_mfma_f32_16x16x32_bf16 v[24:27], v[172:175], v[136:139], v[24:27]
	v_mfma_f32_16x16x32_bf16 v[4:7], v[164:167], v[132:135], v[4:7]
	v_mfma_f32_16x16x32_bf16 v[8:11], v[172:175], v[132:135], v[8:11]
	v_mfma_f32_16x16x32_bf16 v[52:55], v[168:171], v[160:163], v[52:55]
	v_mfma_f32_16x16x32_bf16 v[56:59], v[176:179], v[160:163], v[56:59]
	v_mfma_f32_16x16x32_bf16 v[36:39], v[168:171], v[156:159], v[36:39]
	v_mfma_f32_16x16x32_bf16 v[40:43], v[176:179], v[156:159], v[40:43]
	v_mfma_f32_16x16x32_bf16 v[20:23], v[168:171], v[152:155], v[20:23]
	v_mfma_f32_16x16x32_bf16 v[24:27], v[176:179], v[152:155], v[24:27]
	v_mfma_f32_16x16x32_bf16 v[4:7], v[168:171], v[148:151], v[4:7]
	v_mfma_f32_16x16x32_bf16 v[8:11], v[176:179], v[148:151], v[8:11]
	s_setprio 0
.LBB0_1323:
	s_add_i32 s76, 0, 0x18000
	s_waitcnt lgkmcnt(0)
	v_add_u32_e32 v132, s76, v220
	s_barrier
	ds_read_b128 v[180:183], v132
	ds_read_b128 v[184:187], v132 offset:1024
	ds_read_b128 v[188:191], v132 offset:2048
	ds_read_b128 v[192:195], v132 offset:3072
	s_add_u32 s40, s40, 0x40000
	s_addc_u32 s41, s41, 0
	s_mov_b32 m0, s48
	v_lshl_add_u64 v[164:165], s[40:41], 0, v[206:207]
	ds_read_b128 v[144:147], v221 offset:32768
	ds_read_b128 v[160:163], v221 offset:33792
	ds_read_b128 v[140:143], v221 offset:34816
	ds_read_b128 v[156:159], v221 offset:35840
	ds_read_b128 v[136:139], v221 offset:36864
	ds_read_b128 v[152:155], v221 offset:37888
	ds_read_b128 v[132:135], v221 offset:38912
	ds_read_b128 v[148:151], v221 offset:39936
	global_load_lds_dwordx4 v[164:165], off
	v_lshl_add_u64 v[164:165], s[40:41], 0, v[208:209]
	s_mov_b32 m0, s49
	s_nop 0
	global_load_lds_dwordx4 v[164:165], off
	s_waitcnt lgkmcnt(8)
	s_barrier
	s_waitcnt lgkmcnt(0)
	s_setprio 1
	s_waitcnt lgkmcnt(0)
	v_mfma_f32_16x16x32_bf16 v[124:127], v[180:183], v[144:147], v[124:127]
	v_mfma_f32_16x16x32_bf16 v[128:131], v[188:191], v[144:147], v[128:131]
	v_mfma_f32_16x16x32_bf16 v[108:111], v[180:183], v[140:143], v[108:111]
	v_mfma_f32_16x16x32_bf16 v[112:115], v[188:191], v[140:143], v[112:115]
	v_mfma_f32_16x16x32_bf16 v[92:95], v[180:183], v[136:139], v[92:95]
	v_mfma_f32_16x16x32_bf16 v[96:99], v[188:191], v[136:139], v[96:99]
	v_mfma_f32_16x16x32_bf16 v[76:79], v[180:183], v[132:135], v[76:79]
	v_mfma_f32_16x16x32_bf16 v[80:83], v[188:191], v[132:135], v[80:83]
	v_mfma_f32_16x16x32_bf16 v[124:127], v[184:187], v[160:163], v[124:127]
	v_mfma_f32_16x16x32_bf16 v[128:131], v[192:195], v[160:163], v[128:131]
	v_mfma_f32_16x16x32_bf16 v[108:111], v[184:187], v[156:159], v[108:111]
	v_mfma_f32_16x16x32_bf16 v[112:115], v[192:195], v[156:159], v[112:115]
	v_mfma_f32_16x16x32_bf16 v[92:95], v[184:187], v[152:155], v[92:95]
	v_mfma_f32_16x16x32_bf16 v[96:99], v[192:195], v[152:155], v[96:99]
	v_mfma_f32_16x16x32_bf16 v[76:79], v[184:187], v[148:151], v[76:79]
	v_mfma_f32_16x16x32_bf16 v[80:83], v[192:195], v[148:151], v[80:83]
	s_setprio 0
	s_barrier
	s_add_i32 s40, s76, s3
	v_add_u32_e32 v0, 0x1c000, v0
	v_lshl_add_u64 v[2:3], v[2:3], 0, s[58:59]
	s_mov_b32 m0, s40
	ds_read_b128 v[164:167], v0
	ds_read_b128 v[168:171], v0 offset:1024
	ds_read_b128 v[172:175], v0 offset:2048
	ds_read_b128 v[176:179], v0 offset:3072
	global_load_lds_dwordx4 v[2:3], off
	v_lshl_add_u64 v[2:3], v[214:215], 0, s[58:59]
	s_add_i32 m0, s40, 0x2000
	s_nop 0
	global_load_lds_dwordx4 v[2:3], off
	s_barrier
	s_waitcnt lgkmcnt(0)
	s_setprio 1
	s_waitcnt lgkmcnt(0)
	v_mfma_f32_16x16x32_bf16 v[116:119], v[164:167], v[144:147], v[116:119]
	v_mfma_f32_16x16x32_bf16 v[120:123], v[172:175], v[144:147], v[120:123]
	v_mfma_f32_16x16x32_bf16 v[100:103], v[164:167], v[140:143], v[100:103]
	v_mfma_f32_16x16x32_bf16 v[104:107], v[172:175], v[140:143], v[104:107]
	v_mfma_f32_16x16x32_bf16 v[84:87], v[164:167], v[136:139], v[84:87]
	v_mfma_f32_16x16x32_bf16 v[88:91], v[172:175], v[136:139], v[88:91]
	v_mfma_f32_16x16x32_bf16 v[72:75], v[164:167], v[132:135], v[72:75]
	v_mfma_f32_16x16x32_bf16 v[68:71], v[172:175], v[132:135], v[68:71]
	v_mfma_f32_16x16x32_bf16 v[116:119], v[168:171], v[160:163], v[116:119]
	v_mfma_f32_16x16x32_bf16 v[120:123], v[176:179], v[160:163], v[120:123]
	v_mfma_f32_16x16x32_bf16 v[100:103], v[168:171], v[156:159], v[100:103]
	v_mfma_f32_16x16x32_bf16 v[104:107], v[176:179], v[156:159], v[104:107]
	v_mfma_f32_16x16x32_bf16 v[84:87], v[168:171], v[152:155], v[84:87]
	v_mfma_f32_16x16x32_bf16 v[88:91], v[176:179], v[152:155], v[88:91]
	v_mfma_f32_16x16x32_bf16 v[72:75], v[168:171], v[148:151], v[72:75]
	v_mfma_f32_16x16x32_bf16 v[68:71], v[176:179], v[148:151], v[68:71]
	s_setprio 0
	s_cmp_eq_u32 s101, 1
	s_cbranch_scc0 .Lp8rx_c
	s_waitcnt vmcnt(10)
.Lp8rx_c:
	s_and_b64 vcc, exec, s[14:15]
	s_barrier
	s_cbranch_vccnz .LBB0_1325
	ds_read_b128 v[144:147], v221 offset:49152
	ds_read_b128 v[160:163], v221 offset:50176
	ds_read_b128 v[140:143], v221 offset:51200
	ds_read_b128 v[156:159], v221 offset:52224
	ds_read_b128 v[136:139], v221 offset:53248
	ds_read_b128 v[152:155], v221 offset:54272
	ds_read_b128 v[132:135], v221 offset:55296
	ds_read_b128 v[148:151], v221 offset:56320

; __device__ __forceinline__ unsigned pk_bf16(float lo, float hi) { unsigned r; asm volatile("v_cvt_pk_bf16_f32 %0, %1, %2" : "=v"(r) : "v"(lo), "v"(hi)); return r; }
;     __device__ __forceinline__ void operator()(const f32x4 (&acc)[2][2][4][2], const Unit& u, int wr, int wc, int fr, int fq) const {
;         const int row0 = wr * 64 + fr, col0 = wc * 32 + 8 * fq;
; #pragma unroll
;         for (int ai = 0; ai < 2; ++ai) if (ai == 0 || u.half == 0)
; #pragma unroll
;             for (int m = 0; m < 4; ++m) { bf16_t* rowp = (bf16_t*)u.o + (size_t)(row0 + ai * HALF + m * 16) * u.ldo + col0; float r[8];
; #pragma unroll
;                 for (int bj = 0; bj < 2; ++bj) { const f32x4 a = acc[ai][bj][m][0], b = acc[ai][bj][m][1];
; #pragma unroll
;                     for (int e = 0; e < 4; ++e) r[bj * 4 + e] = a[e] * b[e] * __builtin_amdgcn_rcpf(1.f + __expf(-a[e])); }
;                 u32x4 w; w.x = pk_bf16(r[0], r[1]); w.y = pk_bf16(r[2], r[3]); w.z = pk_bf16(r[4], r[5]); w.w = pk_bf16(r[6], r[7]); st16_wt(rowp, w); }
;     }
.LBB0_1329:
	s_mov_b32 s101, 1
	v_mul_f32_e32 v64, v64, v60
	v_mul_f32_e32 v60, 0xbfb8aa3b, v60
	v_exp_f32_e32 v60, v60
	v_mul_f32_e32 v48, v48, v44
	v_mul_f32_e32 v44, 0xbfb8aa3b, v44
	v_exp_f32_e32 v44, v44
	v_add_f32_e32 v60, 1.0, v60
	v_rcp_f32_e32 v60, v60
	v_mul_f32_e32 v32, v32, v28
	v_mul_f32_e32 v28, 0xbfb8aa3b, v28
	v_exp_f32_e32 v28, v28
	v_add_f32_e32 v44, 1.0, v44
	v_rcp_f32_e32 v44, v44
	v_mul_f32_e32 v60, v64, v60
	v_mul_f32_e32 v64, v65, v61
	v_mul_f32_e32 v61, 0xbfb8aa3b, v61
	v_exp_f32_e32 v61, v61
	v_add_f32_e32 v28, 1.0, v28
	v_rcp_f32_e32 v28, v28
	v_mul_f32_e32 v44, v48, v44
	v_mul_f32_e32 v48, v49, v45
	v_mul_f32_e32 v45, 0xbfb8aa3b, v45
	v_exp_f32_e32 v45, v45
	v_add_f32_e32 v61, 1.0, v61
	v_rcp_f32_e32 v61, v61
	v_mul_f32_e32 v28, v32, v28
	v_mul_f32_e32 v32, v33, v29
	v_mul_f32_e32 v29, 0xbfb8aa3b, v29
	v_exp_f32_e32 v29, v29
	v_add_f32_e32 v45, 1.0, v45
	v_rcp_f32_e32 v45, v45
	v_mul_f32_e32 v61, v64, v61
	v_mul_f32_e32 v64, v66, v62
	v_mul_f32_e32 v62, 0xbfb8aa3b, v62
	v_exp_f32_e32 v62, v62
	v_add_f32_e32 v29, 1.0, v29
	v_rcp_f32_e32 v29, v29
	v_mul_f32_e32 v45, v48, v45
	v_mul_f32_e32 v48, v50, v46
	v_mul_f32_e32 v46, 0xbfb8aa3b, v46
	v_exp_f32_e32 v46, v46
	v_add_f32_e32 v62, 1.0, v62
	v_rcp_f32_e32 v62, v62
	v_mul_f32_e32 v29, v32, v29
	v_mul_f32_e32 v32, v34, v30
	v_mul_f32_e32 v30, 0xbfb8aa3b, v30
	v_exp_f32_e32 v30, v30
	v_add_f32_e32 v46, 1.0, v46
	v_rcp_f32_e32 v46, v46
	v_mul_f32_e32 v62, v64, v62
	v_mul_f32_e32 v64, v67, v63
	v_mul_f32_e32 v63, 0xbfb8aa3b, v63
	v_mul_f32_e32 v56, v56, v52
	v_mul_f32_e32 v52, 0xbfb8aa3b, v52
	v_exp_f32_e32 v63, v63
	v_exp_f32_e32 v52, v52
	v_add_f32_e32 v30, 1.0, v30
	v_rcp_f32_e32 v30, v30
	v_mul_f32_e32 v46, v48, v46
	v_mul_f32_e32 v48, v51, v47
	v_mul_f32_e32 v47, 0xbfb8aa3b, v47
	v_mul_f32_e32 v40, v40, v36
	v_mul_f32_e32 v36, 0xbfb8aa3b, v36
	v_exp_f32_e32 v47, v47
	v_exp_f32_e32 v36, v36
	v_add_f32_e32 v63, 1.0, v63
	v_add_f32_e32 v52, 1.0, v52
	v_rcp_f32_e32 v63, v63
	v_rcp_f32_e32 v52, v52
	v_mul_f32_e32 v30, v32, v30
	v_mul_f32_e32 v32, v35, v31
	v_mul_f32_e32 v31, 0xbfb8aa3b, v31
	v_mul_f32_e32 v24, v24, v20
	v_mul_f32_e32 v20, 0xbfb8aa3b, v20
	v_exp_f32_e32 v31, v31
	v_exp_f32_e32 v20, v20
	v_add_f32_e32 v47, 1.0, v47
	v_add_f32_e32 v36, 1.0, v36
	v_rcp_f32_e32 v47, v47
	v_rcp_f32_e32 v36, v36
	v_mul_f32_e32 v8, v8, v4
	v_mul_f32_e32 v4, 0xbfb8aa3b, v4
	v_mul_f32_e32 v63, v64, v63
	v_mul_f32_e32 v64, v56, v52
	v_mul_f32_e32 v52, v57, v53
	v_mul_f32_e32 v53, 0xbfb8aa3b, v53
	v_mul_f32_e32 v16, v16, v12
	v_mul_f32_e32 v12, 0xbfb8aa3b, v12
	v_exp_f32_e32 v4, v4
	v_exp_f32_e32 v53, v53
	v_add_f32_e32 v31, 1.0, v31
	v_add_f32_e32 v20, 1.0, v20
	v_exp_f32_e32 v12, v12
	v_rcp_f32_e32 v31, v31
	v_rcp_f32_e32 v20, v20
	v_mul_f32_e32 v47, v48, v47
	v_mul_f32_e32 v48, v40, v36
	v_mul_f32_e32 v36, v41, v37
	v_mul_f32_e32 v37, 0xbfb8aa3b, v37
	v_exp_f32_e32 v37, v37
	v_add_f32_e32 v4, 1.0, v4
	v_add_f32_e32 v53, 1.0, v53
	v_add_f32_e32 v12, 1.0, v12
	v_rcp_f32_e32 v4, v4
	v_rcp_f32_e32 v53, v53
	v_mul_f32_e32 v31, v32, v31
	v_mul_f32_e32 v32, v24, v20
	v_mul_f32_e32 v20, v25, v21
	v_mul_f32_e32 v21, 0xbfb8aa3b, v21
	v_rcp_f32_e32 v12, v12
	v_exp_f32_e32 v21, v21
	v_add_f32_e32 v37, 1.0, v37
	v_rcp_f32_e32 v37, v37
	v_mul_f32_e32 v4, v8, v4
	v_mul_f32_e32 v8, v9, v5
	v_mul_f32_e32 v5, 0xbfb8aa3b, v5
	v_mul_f32_e32 v65, v52, v53
	v_mul_f32_e32 v53, 0xbfb8aa3b, v54
	v_mul_f32_e32 v12, v16, v12
	v_mul_f32_e32 v16, v17, v13
	v_mul_f32_e32 v13, 0xbfb8aa3b, v13
	v_exp_f32_e32 v5, v5
	v_exp_f32_e32 v53, v53
	v_add_f32_e32 v21, 1.0, v21
	v_exp_f32_e32 v13, v13
	v_rcp_f32_e32 v21, v21
	v_mul_f32_e32 v49, v36, v37
	v_mul_f32_e32 v37, 0xbfb8aa3b, v38
	v_exp_f32_e32 v37, v37
	v_add_f32_e32 v5, 1.0, v5
	v_add_f32_e32 v53, 1.0, v53
	v_add_f32_e32 v13, 1.0, v13
	v_rcp_f32_e32 v5, v5
	v_rcp_f32_e32 v53, v53
	v_mul_f32_e32 v33, v20, v21
	v_mul_f32_e32 v21, 0xbfb8aa3b, v22
	v_rcp_f32_e32 v13, v13
	v_exp_f32_e32 v21, v21
	v_add_f32_e32 v37, 1.0, v37
	v_mul_f32_e32 v52, v58, v54
	v_rcp_f32_e32 v37, v37
	v_mul_f32_e32 v5, v8, v5
	v_mul_f32_e32 v8, v10, v6
	v_mul_f32_e32 v6, 0xbfb8aa3b, v6
	v_mul_f32_e32 v58, v52, v53
	v_mul_f32_e32 v53, 0xbfb8aa3b, v55
	v_mul_f32_e32 v13, v16, v13
	v_mul_f32_e32 v16, v18, v14
	v_mul_f32_e32 v14, 0xbfb8aa3b, v14
	v_exp_f32_e32 v6, v6
	v_exp_f32_e32 v53, v53
	v_add_f32_e32 v21, 1.0, v21
	v_exp_f32_e32 v14, v14
	v_mul_f32_e32 v36, v42, v38
	v_rcp_f32_e32 v21, v21
	v_mul_f32_e32 v42, v36, v37
	v_mul_f32_e32 v37, 0xbfb8aa3b, v39
	v_exp_f32_e32 v37, v37
	v_add_f32_e32 v6, 1.0, v6
	v_add_f32_e32 v53, 1.0, v53
	v_mul_f32_e32 v20, v26, v22
	v_add_f32_e32 v14, 1.0, v14
	v_rcp_f32_e32 v6, v6
	v_rcp_f32_e32 v53, v53
	v_mul_f32_e32 v26, v20, v21
	v_mul_f32_e32 v21, 0xbfb8aa3b, v23
	v_rcp_f32_e32 v14, v14
	v_exp_f32_e32 v21, v21
	v_add_u32_e32 v68, 0x80, v132
	v_mov_b64_e32 v[2:3], s[30:31]
	s_movk_i32 s14, 0x1600
	v_add_f32_e32 v37, 1.0, v37
	v_mad_i64_i32 v[68:69], s[4:5], v68, s14, v[2:3]
	v_mul_f32_e32 v52, v59, v55
	v_rcp_f32_e32 v37, v37
	v_mul_f32_e32 v8, v8, v6
	v_mul_f32_e32 v6, v11, v7
	v_mul_f32_e32 v7, 0xbfb8aa3b, v7
	v_mul_f32_e32 v55, v52, v53
	v_lshl_add_u64 v[56:57], v[68:69], 0, v[0:1]
	v_cvt_pk_bf16_f32 v52, v60, v61
	v_mul_f32_e32 v14, v16, v14
	v_mul_f32_e32 v16, v19, v15
	v_mul_f32_e32 v15, 0xbfb8aa3b, v15
	v_exp_f32_e32 v7, v7
	v_cvt_pk_bf16_f32 v53, v62, v63
	v_cvt_pk_bf16_f32 v54, v64, v65
	v_cvt_pk_bf16_f32 v55, v58, v55
	global_store_dwordx4 v[56:57], v[52:55], off
	v_add_f32_e32 v21, 1.0, v21
	v_exp_f32_e32 v15, v15
	v_add_u32_e32 v52, 0x90, v132
	v_mad_i64_i32 v[52:53], s[4:5], v52, s14, v[2:3]
	v_mul_f32_e32 v36, v43, v39
	v_rcp_f32_e32 v21, v21
	v_mul_f32_e32 v39, v36, v37
	v_lshl_add_u64 v[40:41], v[52:53], 0, v[0:1]
	v_cvt_pk_bf16_f32 v36, v44, v45
	v_cvt_pk_bf16_f32 v37, v46, v47
	v_cvt_pk_bf16_f32 v38, v48, v49
	v_cvt_pk_bf16_f32 v39, v42, v39
	global_store_dwordx4 v[40:41], v[36:39], off
	v_add_f32_e32 v7, 1.0, v7
	v_mul_f32_e32 v20, v27, v23
	v_add_u32_e32 v36, 0xa0, v132
	v_mad_i64_i32 v[36:37], s[4:5], v36, s14, v[2:3]
	v_add_f32_e32 v15, 1.0, v15
	v_rcp_f32_e32 v7, v7
	v_mul_f32_e32 v23, v20, v21
	v_lshl_add_u64 v[24:25], v[36:37], 0, v[0:1]
	v_cvt_pk_bf16_f32 v20, v28, v29
	v_rcp_f32_e32 v15, v15
	v_cvt_pk_bf16_f32 v21, v30, v31
	v_cvt_pk_bf16_f32 v22, v32, v33
	v_cvt_pk_bf16_f32 v23, v26, v23
	global_store_dwordx4 v[24:25], v[20:23], off
	v_mul_f32_e32 v9, v6, v7
	v_mul_f32_e32 v15, v16, v15
	v_add_u32_e32 v20, 0xb0, v132
	v_mad_i64_i32 v[2:3], s[4:5], v20, s14, v[2:3]
	v_lshl_add_u64 v[6:7], v[2:3], 0, v[0:1]
	v_cvt_pk_bf16_f32 v2, v12, v13
	v_cvt_pk_bf16_f32 v3, v14, v15
	v_cvt_pk_bf16_f32 v4, v4, v5
	v_cvt_pk_bf16_f32 v5, v8, v9
	global_store_dwordx4 v[6:7], v[2:5], off
	s_branch .LBB0_1305
